# attention steady loop: K/V DMA issue moved from after the QK section into QK gaps 2-4
# baseline (speedup 1.0000x reference)
.LBB0_1277:
	s_lshl_b32 s18, s23, 1
	v_mfma_f32_32x32x16_bf16 v[112:127], v[188:191], v[156:159], v[238:253]
	v_add_u32_e32 v237, s18, v214
	ds_read_b64_tr_b16 v[192:193], v237 offset:24576
	v_add_f32_e32 v128, v80, v81
	v_add_f32_e32 v128, v82, v128
	v_add_f32_e32 v128, v83, v128
	v_add_f32_e32 v128, v84, v128
	v_add_f32_e32 v128, v85, v128
	v_cvt_pk_bf16_f32 v148, v80, v81
	v_cvt_pk_bf16_f32 v149, v82, v83
	ds_read_b64_tr_b16 v[194:195], v237 offset:25088
	s_waitcnt lgkmcnt(8)
	v_mfma_f32_32x32x16_bf16 v[112:127], v[180:183], v[152:155], v[112:127]
	s_add_u32 s30, s98, 0xffffe000
	s_addc_u32 s31, s99, -1
	s_add_i32 s18, s86, s89
	s_nop 0
	s_mov_b32 s23, m0
	s_mov_b32 m0, s18
	s_nop 0
	global_load_lds_dwordx4 v196, s[30:31]
	s_mov_b32 m0, s23
	v_add_f32_e32 v80, v86, v128
	v_add_f32_e32 v80, v87, v80
	v_add_f32_e32 v80, v88, v80
	v_add_f32_e32 v82, v89, v80
	v_cvt_pk_bf16_f32 v150, v84, v85
	v_cvt_pk_bf16_f32 v151, v86, v87
	ds_read_b64_tr_b16 v[80:81], v237 offset:28672
	s_waitcnt lgkmcnt(8)
	v_mfma_f32_32x32x16_bf16 v[112:127], v[172:175], v[144:147], v[112:127]
	s_add_u32 s30, s100, 0xffffc000
	s_addc_u32 s31, s101, -1
	s_lshl_b32 s18, s37, 1
	s_add_i32 s18, s18, s90
	s_mov_b32 s23, m0
	s_mov_b32 m0, s18
	s_nop 0
	global_load_lds_dwordx4 v196, s[30:31]
	s_mov_b32 m0, s23
	v_add_f32_e32 v82, v90, v82
	v_add_f32_e32 v82, v91, v82
	v_add_f32_e32 v82, v92, v82
	v_add_f32_e32 v84, v93, v82
	v_cvt_pk_bf16_f32 v140, v88, v89
	v_cvt_pk_bf16_f32 v141, v90, v91
	ds_read_b64_tr_b16 v[82:83], v237 offset:29184
	s_waitcnt lgkmcnt(8)
	v_mfma_f32_32x32x16_bf16 v[112:127], v[164:167], v[136:139], v[112:127]
	s_add_u32 s30, s100, 0xffffe000
	s_addc_u32 s31, s101, -1
	s_addk_i32 s18, 0x2000
	s_mov_b32 s23, m0
	s_mov_b32 m0, s18
	s_nop 0
	global_load_lds_dwordx4 v196, s[30:31]
	s_mov_b32 m0, s23
	v_add_f32_e32 v84, v94, v84
	v_add_f32_e32 v84, v95, v84
	v_add_f32_e32 v84, v64, v84
	v_add_f32_e32 v86, v65, v84
	v_cvt_pk_bf16_f32 v142, v92, v93
	v_cvt_pk_bf16_f32 v143, v94, v95
	ds_read_b64_tr_b16 v[84:85], v237 offset:32768
	s_waitcnt lgkmcnt(8)
	v_mfma_f32_32x32x16_bf16 v[96:111], v[184:187], v[156:159], v[238:253]
	v_add_f32_e32 v86, v66, v86
	v_add_f32_e32 v86, v67, v86
	v_add_f32_e32 v86, v68, v86
	v_add_f32_e32 v88, v69, v86
	v_cvt_pk_bf16_f32 v132, v64, v65
	v_cvt_pk_bf16_f32 v133, v66, v67
	ds_read_b64_tr_b16 v[86:87], v237 offset:33280
	s_waitcnt lgkmcnt(8)
	v_mfma_f32_32x32x16_bf16 v[96:111], v[176:179], v[152:155], v[96:111]
	v_add_f32_e32 v64, v70, v88
	v_add_f32_e32 v64, v71, v64
	v_add_f32_e32 v64, v72, v64
	v_add_f32_e32 v66, v73, v64
	v_cvt_pk_bf16_f32 v134, v68, v69
	v_cvt_pk_bf16_f32 v135, v70, v71
	ds_read_b64_tr_b16 v[64:65], v237 offset:36864
	s_waitcnt lgkmcnt(8)
	v_mfma_f32_32x32x16_bf16 v[96:111], v[168:171], v[144:147], v[96:111]
	v_add_f32_e32 v66, v74, v66
	v_add_f32_e32 v66, v75, v66
	v_add_f32_e32 v66, v76, v66
	v_add_f32_e32 v68, v77, v66
	v_cvt_pk_bf16_f32 v128, v72, v73
	v_cvt_pk_bf16_f32 v129, v74, v75
	v_max_f32_e32 v69, v112, v113
	v_max3_f32 v69, v69, v114, v115
	v_max3_f32 v69, v69, v116, v117
	v_max3_f32 v69, v69, v118, v119
	ds_read_b64_tr_b16 v[66:67], v237 offset:37376
	s_waitcnt lgkmcnt(8)
	v_mfma_f32_32x32x16_bf16 v[96:111], v[160:163], v[136:139], v[96:111]
	v_add_f32_e32 v68, v78, v68
	v_add_f32_e32 v68, v79, v68
	v_add_f32_e32 v236, v236, v68
	v_cvt_pk_bf16_f32 v130, v76, v77
	v_cvt_pk_bf16_f32 v131, v78, v79
	v_max3_f32 v69, v69, v120, v121
	v_max3_f32 v69, v69, v122, v123
	v_max3_f32 v69, v69, v124, v125
	v_max3_f32 v69, v69, v126, v127
	v_max_f32_e32 v70, v96, v97
	v_max3_f32 v70, v70, v98, v99
	v_max3_f32 v70, v70, v100, v101
	v_max3_f32 v70, v70, v102, v103
	v_max3_f32 v70, v70, v104, v105
	v_max3_f32 v70, v70, v106, v107
	v_max3_f32 v70, v70, v108, v109
	v_max3_f32 v70, v70, v110, v111
	v_max_f32_e32 v68, v69, v70
	v_cmp_lt_f32_e32 vcc, s71, v68
	s_cmp_lg_u64 vcc, 0
	s_cselect_b64 s[50:51], -1, 0
	s_cbranch_vccnz .LBB0_1285

.LBB0_1280:
	s_add_i32 s18, s37, 0x2000
	s_lshl_b32 s23, s86, 1
	v_mfma_f32_32x32x16_bf16 v[80:95], v[192:195], v[156:159], v[238:253]
	v_add_u32_e32 v237, s23, v214
	ds_read_b64_tr_b16 v[180:181], v237 offset:24576
	s_cmpk_lg_i32 s37, 0x4000
	s_cselect_b32 s86, s18, 0
	v_add_f32_e32 v128, v112, v113
	v_add_f32_e32 v128, v114, v128
	v_add_f32_e32 v128, v115, v128
	v_add_f32_e32 v128, v116, v128
	v_add_f32_e32 v128, v117, v128
	v_cvt_pk_bf16_f32 v148, v112, v113
	v_cvt_pk_bf16_f32 v149, v114, v115
	ds_read_b64_tr_b16 v[182:183], v237 offset:25088
	s_waitcnt lgkmcnt(8)
	v_mfma_f32_32x32x16_bf16 v[80:95], v[184:187], v[152:155], v[80:95]
	s_add_i32 s18, s37, s89
	s_mov_b32 s23, m0
	s_mov_b32 m0, s18
	s_nop 0
	global_load_lds_dwordx4 v196, s[98:99]
	s_mov_b32 m0, s23
	v_add_f32_e32 v112, v118, v128
	v_add_f32_e32 v112, v119, v112
	v_add_f32_e32 v112, v120, v112
	v_add_f32_e32 v114, v121, v112
	v_cvt_pk_bf16_f32 v150, v116, v117
	v_cvt_pk_bf16_f32 v151, v118, v119
	ds_read_b64_tr_b16 v[112:113], v237 offset:28672
	s_waitcnt lgkmcnt(8)
	v_mfma_f32_32x32x16_bf16 v[80:95], v[172:175], v[144:147], v[80:95]
	s_lshl_b32 s18, s86, 1
	s_add_i32 s18, s18, s90
	s_mov_b32 s23, m0
	s_mov_b32 m0, s18
	s_nop 0
	global_load_lds_dwordx4 v196, s[100:101]
	s_mov_b32 m0, s23
	v_add_f32_e32 v114, v122, v114
	v_add_f32_e32 v114, v123, v114
	v_add_f32_e32 v114, v124, v114
	v_add_f32_e32 v116, v125, v114
	v_cvt_pk_bf16_f32 v140, v120, v121
	v_cvt_pk_bf16_f32 v141, v122, v123
	ds_read_b64_tr_b16 v[114:115], v237 offset:29184
	s_waitcnt lgkmcnt(8)
	v_mfma_f32_32x32x16_bf16 v[80:95], v[164:167], v[136:139], v[80:95]
	s_add_u32 s30, s100, 0x2000
	s_addc_u32 s31, s101, 0
	s_addk_i32 s18, 0x2000
	s_mov_b32 s23, m0
	s_mov_b32 m0, s18
	s_nop 0
	global_load_lds_dwordx4 v196, s[30:31]
	s_mov_b32 m0, s23
	v_add_f32_e32 v116, v126, v116
	v_add_f32_e32 v116, v127, v116
	v_add_f32_e32 v116, v96, v116
	v_add_f32_e32 v118, v97, v116
	v_cvt_pk_bf16_f32 v142, v124, v125
	v_cvt_pk_bf16_f32 v143, v126, v127
	ds_read_b64_tr_b16 v[116:117], v237 offset:32768
	s_waitcnt lgkmcnt(8)
	v_mfma_f32_32x32x16_bf16 v[64:79], v[188:191], v[156:159], v[238:253]
	v_add_f32_e32 v118, v98, v118
	v_add_f32_e32 v118, v99, v118
	v_add_f32_e32 v118, v100, v118
	v_add_f32_e32 v120, v101, v118
	v_cvt_pk_bf16_f32 v132, v96, v97
	v_cvt_pk_bf16_f32 v133, v98, v99
	ds_read_b64_tr_b16 v[118:119], v237 offset:33280
	s_waitcnt lgkmcnt(8)
	v_mfma_f32_32x32x16_bf16 v[64:79], v[176:179], v[152:155], v[64:79]
	v_add_f32_e32 v96, v102, v120
	v_add_f32_e32 v96, v103, v96
	v_add_f32_e32 v96, v104, v96
	v_add_f32_e32 v98, v105, v96
	v_cvt_pk_bf16_f32 v134, v100, v101
	v_cvt_pk_bf16_f32 v135, v102, v103
	ds_read_b64_tr_b16 v[96:97], v237 offset:36864
	s_waitcnt lgkmcnt(8)
	v_mfma_f32_32x32x16_bf16 v[64:79], v[168:171], v[144:147], v[64:79]
	v_add_f32_e32 v98, v106, v98
	v_add_f32_e32 v98, v107, v98
	v_add_f32_e32 v98, v108, v98
	v_add_f32_e32 v100, v109, v98
	v_cvt_pk_bf16_f32 v128, v104, v105
	v_cvt_pk_bf16_f32 v129, v106, v107
	v_max_f32_e32 v101, v80, v81
	v_max3_f32 v101, v101, v82, v83
	v_max3_f32 v101, v101, v84, v85
	v_max3_f32 v101, v101, v86, v87
	ds_read_b64_tr_b16 v[98:99], v237 offset:37376
	s_waitcnt lgkmcnt(8)
	v_mfma_f32_32x32x16_bf16 v[64:79], v[160:163], v[136:139], v[64:79]
	v_add_f32_e32 v100, v110, v100
	v_add_f32_e32 v100, v111, v100
	v_add_f32_e32 v236, v236, v100
	v_cvt_pk_bf16_f32 v130, v108, v109
	v_cvt_pk_bf16_f32 v131, v110, v111
	v_max3_f32 v101, v101, v88, v89
	v_max3_f32 v101, v101, v90, v91
	v_max3_f32 v101, v101, v92, v93
	v_max3_f32 v101, v101, v94, v95
	v_max_f32_e32 v102, v64, v65
	v_max3_f32 v102, v102, v66, v67
	v_max3_f32 v102, v102, v68, v69
	v_max3_f32 v102, v102, v70, v71
	v_max3_f32 v102, v102, v72, v73
	v_max3_f32 v102, v102, v74, v75
	v_max3_f32 v102, v102, v76, v77
	v_max3_f32 v102, v102, v78, v79
	v_max_f32_e32 v100, v101, v102
	v_cmp_lt_f32_e32 vcc, s71, v100
	s_cmp_lg_u64 vcc, 0
	s_cselect_b64 s[50:51], -1, 0
	s_cbranch_vccnz .LBB0_1288
